# as diet3b, cross-half max combine (mov/permlane/max) moved from every tile into the rare rescale path: the any-lane vote does not need it
# speedup vs baseline: 1.0105x; 1.0105x over previous
.Lmla_odd:
	global_load_dwordx4 v[104:107], v154, s[98:99]
	s_mov_b64 exec, s[8:9]
	global_load_dwordx4 v[108:111], v156, s[98:99]
	s_mov_b64 exec, -1
	global_load_dwordx4 v[112:115], v158, s[100:101]
	s_add_u32 s98, s98, 0x18000
	s_addc_u32 s99, s99, 0
	s_add_u32 s100, s100, 0x80
	s_addc_u32 s101, s101, 0
	ds_read_b128 v[48:51], v169 offset:13312
	ds_read_b128 v[52:55], v169 offset:13344
	ds_read_b128 v[116:119], v169 offset:19968
	ds_read_b128 v[120:123], v169 offset:20000
	s_waitcnt lgkmcnt(3)
	v_mfma_f32_32x32x16_bf16 v[64:79], v[48:51], v[100:103], v[32:47]
	ds_read_b128 v[124:127], v169 offset:13376
	ds_read_b128 v[128:131], v169 offset:13408
	ds_read_b128 v[132:135], v169 offset:20032
	ds_read_b128 v[136:139], v169 offset:20064
	s_waitcnt lgkmcnt(4)
	v_mfma_f32_32x32x16_bf16 v[64:79], v[52:55], v[96:99], v[64:79]
	v_mfma_f32_32x32x16_bf16 v[48:63], v[116:119], v[100:103], v[32:47]
	v_mfma_f32_32x32x16_bf16 v[48:63], v[120:123], v[96:99], v[48:63]
	s_waitcnt lgkmcnt(1)
	v_mfma_f32_32x32x16_bf16 v[64:79], v[124:127], v[92:95], v[64:79]
	v_mfma_f32_32x32x16_bf16 v[48:63], v[132:135], v[92:95], v[48:63]
	v_mfma_f32_32x32x16_bf16 v[64:79], v[128:131], v[88:91], v[64:79]
	ds_read_b128 v[116:119], v169 offset:13440
	ds_read_b128 v[120:123], v169 offset:13472
	ds_read_b128 v[128:131], v169 offset:20096
	ds_read_b128 v[176:179], v169 offset:20128
	s_waitcnt lgkmcnt(3)
	v_mfma_f32_32x32x16_bf16 v[48:63], v[136:139], v[88:91], v[48:63]
	v_mfma_f32_32x32x16_bf16 v[64:79], v[116:119], v[84:87], v[64:79]
	s_mulk_i32 s21, 0x2400
	v_add_u32_e32 v116, s21, v170
	ds_read_b128 v[136:139], v116 offset:26624
	ds_read_b128 v[124:127], v116 offset:26656
	s_waitcnt lgkmcnt(3)
	v_mfma_f32_32x32x16_bf16 v[48:63], v[128:131], v[84:87], v[48:63]
	v_mfma_f32_32x32x16_bf16 v[64:79], v[120:123], v[80:83], v[64:79]
	ds_read_b128 v[132:135], v116 offset:26688
	ds_read_b128 v[120:123], v116 offset:26720
	ds_read_b128 v[144:147], v116 offset:31232
	ds_read_b128 v[140:143], v116 offset:31264
	ds_read_b128 v[128:131], v116 offset:31296
	ds_read_b128 v[116:119], v116 offset:31328
	s_waitcnt lgkmcnt(8)
	v_mfma_f32_32x32x16_bf16 v[48:63], v[176:179], v[80:83], v[48:63]
	s_add_i32 s43, s43, 1
	s_nop 10
	v_max_f32_e32 v148, v64, v48
	v_max_f32_e32 v160, v65, v49
	v_max_f32_e32 v161, v67, v51
	v_max3_f32 v176, v66, v50, v70
	v_max3_f32 v161, v161, v71, v55
	v_max3_f32 v148, v148, v68, v52
	v_max3_f32 v160, v160, v69, v53
	v_max3_f32 v176, v176, v54, v74
	v_max3_f32 v161, v161, v75, v59
	v_max3_f32 v148, v148, v72, v56
	v_max3_f32 v160, v160, v73, v57
	v_max3_f32 v176, v176, v58, v78
	v_max3_f32 v161, v161, v79, v63
	v_max3_f32 v148, v148, v76, v60
	v_max3_f32 v160, v160, v77, v61
	v_max3_f32 v161, v176, v62, v161
	v_max3_f32 v148, v148, v160, v161
	v_cmp_lt_f32_e32 vcc, s59, v148
	s_cbranch_vccz .Lmla_norescale_o
	v_mov_b32_e32 v160, v148
	s_nop 1
	v_permlane32_swap_b32_e32 v148, v160
	v_max_f32_e32 v148, v148, v160
	v_max_f32_e32 v32, v148, v148
	v_max_f32_e32 v148, 0, v32
	v_exp_f32_e64 v160, -v148
	v_add_f32_e32 v168, v168, v148
	v_xor_b32_e32 v32, 0x80000000, v168
	v_mov_b32_e32 v33, v32
	v_mov_b32_e32 v34, v32
	v_mov_b32_e32 v35, v32
	v_mov_b32_e32 v36, v32
	v_mov_b32_e32 v37, v32
	v_mov_b32_e32 v38, v32
	v_mov_b32_e32 v39, v32
	v_mov_b32_e32 v40, v32
	v_mov_b32_e32 v41, v32
	v_mov_b32_e32 v42, v32
	v_mov_b32_e32 v43, v32
	v_mov_b32_e32 v44, v32
	v_mov_b32_e32 v45, v32
	v_mov_b32_e32 v46, v32
	v_mov_b32_e32 v47, v32
	v_pk_add_f32 v[64:65], v[64:65], v[148:149] op_sel_hi:[1,0] neg_lo:[0,1] neg_hi:[0,1]
	v_pk_add_f32 v[48:49], v[48:49], v[148:149] op_sel_hi:[1,0] neg_lo:[0,1] neg_hi:[0,1]
	v_pk_add_f32 v[66:67], v[66:67], v[148:149] op_sel_hi:[1,0] neg_lo:[0,1] neg_hi:[0,1]
	v_pk_add_f32 v[50:51], v[50:51], v[148:149] op_sel_hi:[1,0] neg_lo:[0,1] neg_hi:[0,1]
	v_pk_add_f32 v[68:69], v[68:69], v[148:149] op_sel_hi:[1,0] neg_lo:[0,1] neg_hi:[0,1]
	v_pk_add_f32 v[52:53], v[52:53], v[148:149] op_sel_hi:[1,0] neg_lo:[0,1] neg_hi:[0,1]
	v_pk_add_f32 v[70:71], v[70:71], v[148:149] op_sel_hi:[1,0] neg_lo:[0,1] neg_hi:[0,1]
	v_pk_add_f32 v[54:55], v[54:55], v[148:149] op_sel_hi:[1,0] neg_lo:[0,1] neg_hi:[0,1]
	v_pk_add_f32 v[72:73], v[72:73], v[148:149] op_sel_hi:[1,0] neg_lo:[0,1] neg_hi:[0,1]
	v_pk_add_f32 v[56:57], v[56:57], v[148:149] op_sel_hi:[1,0] neg_lo:[0,1] neg_hi:[0,1]
	v_pk_add_f32 v[74:75], v[74:75], v[148:149] op_sel_hi:[1,0] neg_lo:[0,1] neg_hi:[0,1]
	v_pk_add_f32 v[58:59], v[58:59], v[148:149] op_sel_hi:[1,0] neg_lo:[0,1] neg_hi:[0,1]
	v_pk_add_f32 v[76:77], v[76:77], v[148:149] op_sel_hi:[1,0] neg_lo:[0,1] neg_hi:[0,1]
	v_pk_add_f32 v[60:61], v[60:61], v[148:149] op_sel_hi:[1,0] neg_lo:[0,1] neg_hi:[0,1]
	v_pk_add_f32 v[78:79], v[78:79], v[148:149] op_sel_hi:[1,0] neg_lo:[0,1] neg_hi:[0,1]
	v_pk_add_f32 v[62:63], v[62:63], v[148:149] op_sel_hi:[1,0] neg_lo:[0,1] neg_hi:[0,1]
	v_pk_mul_f32 v[30:31], v[30:31], v[160:161] op_sel_hi:[1,0]
	v_pk_mul_f32 v[28:29], v[28:29], v[160:161] op_sel_hi:[1,0]
	v_pk_mul_f32 v[26:27], v[26:27], v[160:161] op_sel_hi:[1,0]
	v_pk_mul_f32 v[24:25], v[24:25], v[160:161] op_sel_hi:[1,0]
	v_pk_mul_f32 v[22:23], v[22:23], v[160:161] op_sel_hi:[1,0]
	v_pk_mul_f32 v[20:21], v[20:21], v[160:161] op_sel_hi:[1,0]
	v_pk_mul_f32 v[18:19], v[18:19], v[160:161] op_sel_hi:[1,0]
	v_pk_mul_f32 v[16:17], v[16:17], v[160:161] op_sel_hi:[1,0]
	v_pk_mul_f32 v[14:15], v[14:15], v[160:161] op_sel_hi:[1,0]
	v_pk_mul_f32 v[12:13], v[12:13], v[160:161] op_sel_hi:[1,0]
	v_pk_mul_f32 v[10:11], v[10:11], v[160:161] op_sel_hi:[1,0]
	v_pk_mul_f32 v[8:9], v[8:9], v[160:161] op_sel_hi:[1,0]
	v_pk_mul_f32 v[6:7], v[6:7], v[160:161] op_sel_hi:[1,0]
	v_pk_mul_f32 v[4:5], v[4:5], v[160:161] op_sel_hi:[1,0]
	v_pk_mul_f32 v[2:3], v[2:3], v[160:161] op_sel_hi:[1,0]
	v_pk_mul_f32 v[0:1], v[0:1], v[160:161] op_sel_hi:[1,0]
	v_pk_mul_f32 v[152:153], v[152:153], v[160:161] op_sel_hi:[1,0]
	v_pk_mul_f32 v[150:151], v[150:151], v[160:161] op_sel_hi:[1,0]
; #define AT_QK_LD0(kb_) do { if constexpr (NEGM) { const LAS unsigned char* kbp_ = Kl + (kb_) * KBUF + r32 * KROWB + hi * 16; AT_KLD2(0); __builtin_amdgcn_sched_barrier(0); } } while (0)
; template <int DQK, int DV, int RH, bool NEGM> ...
;     ...
;     const int NT = nkv / 64;
;     AT_GLOAD(0); AT_LSTORE(0, 0); __syncthreads();
;     int vs_prev = 2, vs_cur = 0, vs_next = 1;
;     if (!grpB) {
;         for (int t = 0; t < NT; ++t) {
;             const int kb = t & 1;
;             if (t + 1 < NT) AT_GLOAD(t + 1);
;             f32x16 p[RH][2];
;             AT_QK_LD0(kb); AT_QK(kb); AT_VLOAD(vs_cur); AT_SOFTMAX(); AT_PV(vs_cur);
;             if (t + 1 < NT) AT_LSTORE(kb ^ 1, vs_next);
;             __syncthreads();
;             vs_prev = vs_cur; vs_cur = vs_next; vs_next = (vs_next == 2) ? 0 : vs_next + 1;
.Lmla_norescale_o:
	v_exp_f32_e32 v160, v64
	v_exp_f32_e32 v161, v65
	v_exp_f32_e32 v64, v66
	v_exp_f32_e32 v65, v67
	v_exp_f32_e32 v68, v68
	v_exp_f32_e32 v69, v69
	v_exp_f32_e32 v66, v70
	v_exp_f32_e32 v67, v71
	v_cvt_pk_bf16_f32 v176, v160, v161
	v_cvt_pk_bf16_f32 v177, v64, v65
	v_cvt_pk_bf16_f32 v178, v68, v69
	v_cvt_pk_bf16_f32 v179, v66, v67
	v_exp_f32_e32 v70, v74
	v_exp_f32_e32 v71, v75
	s_waitcnt lgkmcnt(0)
	v_mfma_f32_32x32x16_bf16 v[16:31], v[136:139], v[176:179], v[16:31]
	v_exp_f32_e32 v136, v72
	v_exp_f32_e32 v137, v73
	v_exp_f32_e32 v74, v76
	v_exp_f32_e32 v75, v77
	v_exp_f32_e32 v72, v78
	v_exp_f32_e32 v73, v79
	v_exp_f32_e32 v76, v48
	v_mfma_f32_32x32x16_bf16 v[0:15], v[144:147], v[176:179], v[0:15]
	v_cvt_pk_bf16_f32 v144, v136, v137
	v_cvt_pk_bf16_f32 v145, v70, v71
	v_cvt_pk_bf16_f32 v146, v74, v75
	v_cvt_pk_bf16_f32 v147, v72, v73
	v_exp_f32_e32 v77, v49
	v_exp_f32_e32 v48, v50
	v_exp_f32_e32 v49, v51
	v_mfma_f32_32x32x16_bf16 v[16:31], v[124:127], v[144:147], v[16:31]
	v_exp_f32_e32 v52, v52
	v_exp_f32_e32 v53, v53
	v_exp_f32_e32 v50, v54
	v_exp_f32_e32 v51, v55
	v_cvt_pk_bf16_f32 v124, v76, v77
	v_cvt_pk_bf16_f32 v125, v48, v49
	v_cvt_pk_bf16_f32 v126, v52, v53
	v_mfma_f32_32x32x16_bf16 v[0:15], v[140:143], v[144:147], v[0:15]
	v_cvt_pk_bf16_f32 v127, v50, v51
	v_exp_f32_e32 v78, v56
	v_exp_f32_e32 v79, v57
	v_exp_f32_e32 v54, v58
	v_exp_f32_e32 v55, v59
	v_exp_f32_e32 v58, v60
	v_exp_f32_e32 v59, v61
	v_mfma_f32_32x32x16_bf16 v[16:31], v[132:135], v[124:127], v[16:31]
	v_exp_f32_e32 v56, v62
	v_exp_f32_e32 v57, v63
	v_cvt_pk_bf16_f32 v60, v78, v79
	v_cvt_pk_bf16_f32 v61, v54, v55
	v_cvt_pk_bf16_f32 v62, v58, v59
	v_cvt_pk_bf16_f32 v63, v56, v57
	v_mfma_f32_32x32x16_bf16 v[0:15], v[128:131], v[124:127], v[0:15]
	v_mfma_f32_32x32x16_bf16 v[16:31], v[120:123], v[60:63], v[16:31]
	v_mfma_f32_32x32x16_bf16 v[0:15], v[116:119], v[60:63], v[0:15]
	s_waitcnt vmcnt(1)
	ds_write_b128 v244, v[104:107]
	s_mov_b64 exec, s[8:9]
	ds_write_b128 v245, v[108:111]
	s_mov_b64 exec, -1
	s_mul_i32 s21, s42, 0x2400
	v_add_u32_e32 v242, s21, v243
	s_waitcnt vmcnt(0)
	ds_write2_b64 v242, v[112:113], v[114:115] offset1:2
	v_pk_add_f32 v[48:49], v[64:65], v[48:49]
	v_pk_add_f32 v[60:61], v[160:161], v[76:77]
	v_pk_add_f32 v[48:49], v[152:153], v[48:49]
	v_pk_add_f32 v[50:51], v[66:67], v[50:51]
	v_pk_add_f32 v[60:61], v[150:151], v[60:61]
	v_pk_add_f32 v[52:53], v[68:69], v[52:53]
	v_pk_add_f32 v[48:49], v[50:51], v[48:49]
	v_pk_add_f32 v[50:51], v[70:71], v[54:55]
	v_pk_add_f32 v[52:53], v[52:53], v[60:61]
	v_pk_add_f32 v[60:61], v[136:137], v[78:79]
	v_pk_add_f32 v[48:49], v[50:51], v[48:49]
	v_pk_add_f32 v[50:51], v[72:73], v[56:57]
	s_add_i32 s40, s42, 1
	v_pk_add_f32 v[52:53], v[60:61], v[52:53]
	v_pk_add_f32 v[58:59], v[74:75], v[58:59]
	v_pk_add_f32 v[152:153], v[50:51], v[48:49]
	s_cmp_lg_u32 s42, 2
	v_pk_add_f32 v[150:151], v[58:59], v[52:53]
	s_cselect_b32 s40, s40, 0
	s_cmp_lg_u32 s43, 63
	s_waitcnt lgkmcnt(0)
	s_barrier
	s_mov_b32 s21, s42
	s_mov_b32 s42, s40
	global_load_dwordx4 v[104:107], v154, s[98:99]
	s_mov_b64 exec, s[8:9]
	global_load_dwordx4 v[108:111], v156, s[98:99]
	s_mov_b64 exec, -1
	global_load_dwordx4 v[112:115], v158, s[100:101]
	s_add_u32 s98, s98, 0x18000
	s_addc_u32 s99, s99, 0
	s_add_u32 s100, s100, 0x80
	s_addc_u32 s101, s101, 0
	ds_read_b128 v[48:51], v169
	ds_read_b128 v[52:55], v169 offset:32
	ds_read_b128 v[116:119], v169 offset:6656
	ds_read_b128 v[120:123], v169 offset:6688
	s_waitcnt lgkmcnt(3)
	v_mfma_f32_32x32x16_bf16 v[64:79], v[48:51], v[100:103], v[32:47]
	ds_read_b128 v[124:127], v169 offset:64
	ds_read_b128 v[128:131], v169 offset:96
	ds_read_b128 v[132:135], v169 offset:6720
	ds_read_b128 v[136:139], v169 offset:6752
	s_waitcnt lgkmcnt(4)
	v_mfma_f32_32x32x16_bf16 v[64:79], v[52:55], v[96:99], v[64:79]
	v_mfma_f32_32x32x16_bf16 v[48:63], v[116:119], v[100:103], v[32:47]
	v_mfma_f32_32x32x16_bf16 v[48:63], v[120:123], v[96:99], v[48:63]
	s_waitcnt lgkmcnt(1)
	v_mfma_f32_32x32x16_bf16 v[64:79], v[124:127], v[92:95], v[64:79]
	v_mfma_f32_32x32x16_bf16 v[48:63], v[132:135], v[92:95], v[48:63]
	v_mfma_f32_32x32x16_bf16 v[64:79], v[128:131], v[88:91], v[64:79]
	ds_read_b128 v[116:119], v169 offset:128
	ds_read_b128 v[120:123], v169 offset:160
	ds_read_b128 v[128:131], v169 offset:6784
	ds_read_b128 v[176:179], v169 offset:6816
	s_waitcnt lgkmcnt(3)
	v_mfma_f32_32x32x16_bf16 v[48:63], v[136:139], v[88:91], v[48:63]
	v_mfma_f32_32x32x16_bf16 v[64:79], v[116:119], v[84:87], v[64:79]
	s_mulk_i32 s21, 0x2400
	v_add_u32_e32 v116, s21, v170
	ds_read_b128 v[136:139], v116 offset:26624
	ds_read_b128 v[124:127], v116 offset:26656
	s_waitcnt lgkmcnt(3)
	v_mfma_f32_32x32x16_bf16 v[48:63], v[128:131], v[84:87], v[48:63]
	v_mfma_f32_32x32x16_bf16 v[64:79], v[120:123], v[80:83], v[64:79]
	ds_read_b128 v[132:135], v116 offset:26688
	ds_read_b128 v[120:123], v116 offset:26720
	ds_read_b128 v[144:147], v116 offset:31232
	ds_read_b128 v[140:143], v116 offset:31264
	ds_read_b128 v[128:131], v116 offset:31296
	ds_read_b128 v[116:119], v116 offset:31328
	s_waitcnt lgkmcnt(8)
	v_mfma_f32_32x32x16_bf16 v[48:63], v[176:179], v[80:83], v[48:63]
	s_add_i32 s43, s43, 1
	s_nop 10
	v_max_f32_e32 v148, v64, v48
	v_max_f32_e32 v160, v65, v49
	v_max_f32_e32 v161, v67, v51
	v_max3_f32 v176, v66, v50, v70
	v_max3_f32 v161, v161, v71, v55
	v_max3_f32 v148, v148, v68, v52
	v_max3_f32 v160, v160, v69, v53
	v_max3_f32 v176, v176, v54, v74
	v_max3_f32 v161, v161, v75, v59
	v_max3_f32 v148, v148, v72, v56
	v_max3_f32 v160, v160, v73, v57
	v_max3_f32 v176, v176, v58, v78
	v_max3_f32 v161, v161, v79, v63
	v_max3_f32 v148, v148, v76, v60
	v_max3_f32 v160, v160, v77, v61
	v_max3_f32 v161, v176, v62, v161
	v_max3_f32 v148, v148, v160, v161
	v_cmp_lt_f32_e32 vcc, s59, v148
	s_cbranch_vccz .Lmla_norescale_e
	v_mov_b32_e32 v160, v148
	s_nop 1
	v_permlane32_swap_b32_e32 v148, v160
	v_max_f32_e32 v148, v148, v160
	v_max_f32_e32 v32, v148, v148
	v_max_f32_e32 v148, 0, v32
	v_exp_f32_e64 v160, -v148
	v_add_f32_e32 v168, v168, v148
	v_xor_b32_e32 v32, 0x80000000, v168
	v_mov_b32_e32 v33, v32
	v_mov_b32_e32 v34, v32
	v_mov_b32_e32 v35, v32
	v_mov_b32_e32 v36, v32
	v_mov_b32_e32 v37, v32
	v_mov_b32_e32 v38, v32
	v_mov_b32_e32 v39, v32
	v_mov_b32_e32 v40, v32
	v_mov_b32_e32 v41, v32
	v_mov_b32_e32 v42, v32
	v_mov_b32_e32 v43, v32
	v_mov_b32_e32 v44, v32
	v_mov_b32_e32 v45, v32
	v_mov_b32_e32 v46, v32
	v_mov_b32_e32 v47, v32
	v_pk_add_f32 v[64:65], v[64:65], v[148:149] op_sel_hi:[1,0] neg_lo:[0,1] neg_hi:[0,1]
	v_pk_add_f32 v[48:49], v[48:49], v[148:149] op_sel_hi:[1,0] neg_lo:[0,1] neg_hi:[0,1]
	v_pk_add_f32 v[66:67], v[66:67], v[148:149] op_sel_hi:[1,0] neg_lo:[0,1] neg_hi:[0,1]
	v_pk_add_f32 v[50:51], v[50:51], v[148:149] op_sel_hi:[1,0] neg_lo:[0,1] neg_hi:[0,1]
	v_pk_add_f32 v[68:69], v[68:69], v[148:149] op_sel_hi:[1,0] neg_lo:[0,1] neg_hi:[0,1]
	v_pk_add_f32 v[52:53], v[52:53], v[148:149] op_sel_hi:[1,0] neg_lo:[0,1] neg_hi:[0,1]
	v_pk_add_f32 v[70:71], v[70:71], v[148:149] op_sel_hi:[1,0] neg_lo:[0,1] neg_hi:[0,1]
	v_pk_add_f32 v[54:55], v[54:55], v[148:149] op_sel_hi:[1,0] neg_lo:[0,1] neg_hi:[0,1]
	v_pk_add_f32 v[72:73], v[72:73], v[148:149] op_sel_hi:[1,0] neg_lo:[0,1] neg_hi:[0,1]
	v_pk_add_f32 v[56:57], v[56:57], v[148:149] op_sel_hi:[1,0] neg_lo:[0,1] neg_hi:[0,1]
	v_pk_add_f32 v[74:75], v[74:75], v[148:149] op_sel_hi:[1,0] neg_lo:[0,1] neg_hi:[0,1]
	v_pk_add_f32 v[58:59], v[58:59], v[148:149] op_sel_hi:[1,0] neg_lo:[0,1] neg_hi:[0,1]
	v_pk_add_f32 v[76:77], v[76:77], v[148:149] op_sel_hi:[1,0] neg_lo:[0,1] neg_hi:[0,1]
	v_pk_add_f32 v[60:61], v[60:61], v[148:149] op_sel_hi:[1,0] neg_lo:[0,1] neg_hi:[0,1]
	v_pk_add_f32 v[78:79], v[78:79], v[148:149] op_sel_hi:[1,0] neg_lo:[0,1] neg_hi:[0,1]
	v_pk_add_f32 v[62:63], v[62:63], v[148:149] op_sel_hi:[1,0] neg_lo:[0,1] neg_hi:[0,1]
	v_pk_mul_f32 v[30:31], v[30:31], v[160:161] op_sel_hi:[1,0]
	v_pk_mul_f32 v[28:29], v[28:29], v[160:161] op_sel_hi:[1,0]
	v_pk_mul_f32 v[26:27], v[26:27], v[160:161] op_sel_hi:[1,0]
	v_pk_mul_f32 v[24:25], v[24:25], v[160:161] op_sel_hi:[1,0]
	v_pk_mul_f32 v[22:23], v[22:23], v[160:161] op_sel_hi:[1,0]
	v_pk_mul_f32 v[20:21], v[20:21], v[160:161] op_sel_hi:[1,0]
	v_pk_mul_f32 v[18:19], v[18:19], v[160:161] op_sel_hi:[1,0]
	v_pk_mul_f32 v[16:17], v[16:17], v[160:161] op_sel_hi:[1,0]
	v_pk_mul_f32 v[14:15], v[14:15], v[160:161] op_sel_hi:[1,0]
	v_pk_mul_f32 v[12:13], v[12:13], v[160:161] op_sel_hi:[1,0]
	v_pk_mul_f32 v[10:11], v[10:11], v[160:161] op_sel_hi:[1,0]
	v_pk_mul_f32 v[8:9], v[8:9], v[160:161] op_sel_hi:[1,0]
	v_pk_mul_f32 v[6:7], v[6:7], v[160:161] op_sel_hi:[1,0]
	v_pk_mul_f32 v[4:5], v[4:5], v[160:161] op_sel_hi:[1,0]
	v_pk_mul_f32 v[2:3], v[2:3], v[160:161] op_sel_hi:[1,0]
	v_pk_mul_f32 v[0:1], v[0:1], v[160:161] op_sel_hi:[1,0]
	v_pk_mul_f32 v[152:153], v[152:153], v[160:161] op_sel_hi:[1,0]
	v_pk_mul_f32 v[150:151], v[150:151], v[160:161] op_sel_hi:[1,0]
